# k10
# baseline (speedup 1.0000x reference)
; #define PHASE(code) PHASE_(code, true)
; __device__ __forceinline__ void attn_phase(const u16* __restrict__ QKVall, u16* __restrict__ Oall, char* shm, const float* __restrict__ qgain, const float* __restrict__ ropetab,
;                                            unsigned sx, unsigned srank, unsigned snloc) {
;   const u16* QKV = (const u16*)((const char*)QKVall + (size_t)sx * SLAB);
;   u16* O = (u16*)((char*)Oall + (size_t)sx * SLAB);
;   for (int it = (int)srank; it < 128; it += (int)snloc) {
;     const int kvh = it >> 6, w = it & 63, hq = kvh * 4 + (w >> 4), qblk = w & 15;
;     const u16* Qb = QKV + (size_t)(qblk * 256) * DQKV + hq * 128;
;     const u16* Kh = QKV + 1024 + kvh * 128;
;     const u16* Vh = QKV + 1280 + kvh * 128;
;     u16* Ob = O + (size_t)(qblk * 256) * DM + hq * 128;
; __global__ void __launch_bounds__(NTHREADS, 2) fwd_megakernel(Params p_unused, int ph0, int ph1) {
;     ...
;           PHASE(char* ws = kp->ws; attn_phase((const u16*)(ws + OFF_QKV), (u16*)(ws + OFF_O), shm_raw, kp->qnorm + jm * 128, (const float*)(ws + OFF_ROPE), sx, srank, snloc));
.LBB0_853:
	s_andn2_b64 vcc, exec, s[4:5]
	s_cbranch_vccnz .LBB0_943
	v_readlane_b32 s0, v240, 10
	v_readlane_b32 s1, v240, 11
	s_andn2_b64 vcc, exec, s[0:1]
	v_readlane_b32 s0, v239, 29
	v_readlane_b32 s1, v239, 30
	s_movk_i32 s20, 0x1000
	v_writelane_b32 v239, s0, 29
	s_nop 1
	v_writelane_b32 v239, s1, 30
	s_cbranch_vccnz .LBB0_876
	v_cmp_lt_u32_e32 vcc, 255, v182
	s_cbranch_vccnz .Lattn_prio_skip
	s_setprio 1
.Lattn_prio_skip:
	v_readlane_b32 s2, v239, 29
	v_readlane_b32 s3, v239, 30
	s_load_dwordx2 s[0:1], s[2:3], 0x80
	s_nop 0
	s_load_dwordx2 s[2:3], s[2:3], 0xa8
	v_readlane_b32 s4, v239, 7
	v_readlane_b32 s5, v239, 8
	s_lshl_b64 s[4:5], s[4:5], 2
	s_waitcnt lgkmcnt(0)
	s_add_u32 s12, s0, s4
	s_addc_u32 s13, s1, s5
	s_add_u32 s14, s2, 0x17f00000
	s_addc_u32 s15, s3, 0
	v_readlane_b32 s0, v238, 63
	s_add_u32 s0, s2, s0
	v_readlane_b32 s1, v238, 55
	s_addc_u32 s1, s3, s1
	s_add_u32 s18, s0, 0x4000000
	s_addc_u32 s19, s1, 0
	s_add_u32 s22, s0, 0x4c00000
	s_addc_u32 s23, s1, 0
	v_readlane_b32 s0, v238, 54
	s_add_u32 s27, s2, s0
	v_readlane_b32 s0, v238, 56
	s_addc_u32 s28, s3, s0
	v_readlane_b32 s0, v238, 39
	s_mov_b32 s29, s0
	v_readlane_b32 s1, v238, 40
	s_branch .LBB0_857

; __device__ __forceinline__ unsigned xb_ld(unsigned* p)              { return __hip_atomic_load(p, __ATOMIC_RELAXED, __HIP_MEMORY_SCOPE_AGENT); }
; __device__ __forceinline__ unsigned xb_add(unsigned* p, unsigned v) { return __hip_atomic_fetch_add(p, v, __ATOMIC_RELAXED, __HIP_MEMORY_SCOPE_AGENT); }
; #define XB_SPIN(cond, bar) do { unsigned _sp = 0; while (cond) { __builtin_amdgcn_s_sleep(1); \
;     if ((++_sp & 255u) == 0u) { if (xb_ld(&(bar)[XB_TMO])) break; if (_sp > XB_SPIN_CAP) { atomicAdd(&(bar)[XB_TMO], 1u); break; } } } } while (0)
; __device__ __forceinline__ void xcd_barrier(XcdBarrier& b) {
;   asm volatile("s_waitcnt vmcnt(0)" ::: "memory");
;   __syncthreads();
;   if (threadIdx.x == 0) {
;     unsigned* bar = b.bar;
;     __builtin_amdgcn_s_waitcnt(0);
;     const unsigned old = xb_add(&bar[XB_XSUB(b.x)], 1u);
;     const unsigned gen = b.round;
;     if (old + 1u == (gen + 1u) * b.nloc) {
;       __builtin_amdgcn_fence(__ATOMIC_RELEASE, "agent");
;       asm volatile("s_waitcnt vmcnt(0)" ::: "memory");
;       const unsigned og = xb_add(&bar[XB_TOP], 1u);
;       const unsigned tg = gen;
;       if (og + 1u == (tg + 1u) * b.nx) xb_add(&bar[XB_TOPGEN], 1u);
;       else XB_SPIN(xb_ld(&bar[XB_TOPGEN]) == tg, bar);
;       __builtin_amdgcn_fence(__ATOMIC_ACQUIRE, "agent");
;       xb_add(&bar[XB_XGEN(b.x)], 1u);
;     } else {
;       XB_SPIN(xb_ld(&bar[XB_XGEN(b.x)]) == gen, bar);
;       __builtin_amdgcn_fence(__ATOMIC_ACQUIRE, "agent");
;     }
;   }
;   b.round += 1u;
;   __syncthreads();
; }
; __device__ __forceinline__ void xcc_barrier(XcdBarrier& b) {
;   asm volatile("s_waitcnt vmcnt(0)" ::: "memory");
;   __syncthreads();
;   if (threadIdx.x == 0) {
;     unsigned* bar = b.bar;
;     __builtin_amdgcn_s_waitcnt(0);
;     const unsigned old = xb_add(&bar[XB_LSUB(b.x)], 1u);
;     const unsigned gen = b.lround;
;     if (old + 1u == (gen + 1u) * b.nloc) xb_add(&bar[XB_LGEN(b.x)], 1u);
;     else XB_SPIN(xb_ld(&bar[XB_LGEN(b.x)]) == gen, bar);
;     __builtin_amdgcn_fence(__ATOMIC_ACQUIRE, "agent");
;   }
;   b.lround += 1u;
;   __syncthreads();
.LBB0_876:
	s_setprio 0
	v_readlane_b32 s8, v240, 4
	v_readlane_b32 s9, v240, 5
	s_add_i32 s0, s52, 3
	s_mov_b64 s[4:5], s[8:9]
	s_cmp_ge_i32 s0, s5
	v_readlane_b32 s10, v240, 6
	v_readlane_b32 s11, v240, 7
	s_cbranch_scc1 .LBB0_893
	s_cmp_lg_u32 s26, s4
	v_readlane_b32 s4, v240, 8
	s_cselect_b64 s[2:3], -1, 0
	v_readlane_b32 s5, v240, 9
	s_and_b64 s[2:3], s[2:3], s[4:5]
	s_andn2_b64 vcc, exec, s[2:3]
	s_mov_b64 s[4:5], -1
	s_movk_i32 s28, 0x1000
	s_cbranch_vccz .LBB0_920
	s_waitcnt vmcnt(0)
	v_readlane_b32 s4, v239, 2
	v_add_u32_e32 v2, 1, v189
	v_readlane_b32 s5, v239, 3
	s_waitcnt lgkmcnt(0)
	s_barrier
	s_and_saveexec_b64 s[2:3], s[4:5]
	s_xor_b64 s[4:5], exec, s[2:3]
	v_add_u32_e32 v2, 1, v189
	s_andn2_saveexec_b64 s[4:5], s[4:5]
	s_cbranch_execz .LBB0_919
	s_mov_b64 s[8:9], exec
	v_mbcnt_lo_u32_b32 v0, s8, 0
	v_mbcnt_hi_u32_b32 v0, s9, v0
	v_cmp_eq_u32_e32 vcc, 0, v0
	s_waitcnt vmcnt(0) expcnt(0) lgkmcnt(0)
	s_and_saveexec_b64 s[10:11], vcc
	s_cbranch_execz .LBB0_883
	s_bcnt1_i32_b64 s1, s[8:9]
	v_readlane_b32 s2, v240, 29
	v_mov_b32_e32 v1, s1
	v_readlane_b32 s3, v240, 30
	s_nop 4
	global_atomic_add v1, v177, v1, s[2:3] sc0
